# grid barriers: non-leader workgroups wait on the cross-XCD release word directly (one hop less on the release path)
# speedup vs baseline: 1.0049x; 1.0049x over previous
; __device__ __forceinline__ unsigned xb_ld(unsigned* p)              { return __hip_atomic_load(p, __ATOMIC_RELAXED, __HIP_MEMORY_SCOPE_AGENT); }
; __device__ __forceinline__ unsigned xb_add(unsigned* p, unsigned v) { return __hip_atomic_fetch_add(p, v, __ATOMIC_RELAXED, __HIP_MEMORY_SCOPE_AGENT); }
; #define XB_SPIN(cond, bar) do { unsigned _sp = 0; while (cond) { __builtin_amdgcn_s_sleep(1); \
;     if ((++_sp & 255u) == 0u) { if (xb_ld(&(bar)[XB_TMO])) break; if (_sp > XB_SPIN_CAP) { atomicAdd(&(bar)[XB_TMO], 1u); break; } } } } while (0)
; __device__ __forceinline__ void xcd_barrier(const XcdBarrier& b) {
;     ...
;         const unsigned old = xb_add(&bar[XB_XSUB(b.x)], 1u);
;         const unsigned gen = old / nloc;
;         if (old + 1u == (gen + 1u) * nloc) {
;             __builtin_amdgcn_fence(__ATOMIC_RELEASE, "agent");
;             asm volatile("s_waitcnt vmcnt(0)" ::: "memory");
;             const unsigned og = xb_add(&bar[XB_TOP], 1u);
;             const unsigned tg = og / nx;
;             if (og + 1u == (tg + 1u) * nx) xb_add(&bar[XB_TOPGEN], 1u);
;             else XB_SPIN(xb_ld(&bar[XB_TOPGEN]) == tg, bar);
;             __builtin_amdgcn_fence(__ATOMIC_ACQUIRE, "agent");
;             xb_add(&bar[XB_XGEN(b.x)], 1u);
;             asm volatile("s_waitcnt vmcnt(0)" ::: "memory");
;         } else {
;             XB_SPIN(xb_ld(&bar[XB_XGEN(b.x)]) == gen, bar);
.LBB0_216:
	s_lshl_b32 s0, s39, 8
	s_add_u32 s0, s38, s0
	s_addc_u32 s1, s37, 0
	v_mov_b32_e32 v1, s0
	v_add_co_u32_e32 v4, vcc, 0x101000, v1
	v_mov_b32_e32 v1, s1
	s_nop 0
	v_addc_co_u32_e32 v5, vcc, 0, v1, vcc
	v_mov_b32_e32 v1, 1
	flat_atomic_add v1, v[4:5], v1 offset:1024 sc0
	v_cvt_f32_u32_e32 v3, v2
	v_sub_u32_e32 v4, 0, v2
	s_add_u32 s27, s0, 0x100000
	s_addc_u32 s26, s1, 0
	v_rcp_iflag_f32_e32 v3, v3
	s_nop 0
	v_mul_f32_e32 v3, 0x4f7ffffe, v3
	v_cvt_u32_f32_e32 v3, v3
	v_mul_lo_u32 v4, v4, v3
	v_mul_hi_u32 v4, v3, v4
	v_add_u32_e32 v3, v3, v4
	s_waitcnt vmcnt(0) lgkmcnt(0)
	v_mul_hi_u32 v3, v1, v3
	v_mul_lo_u32 v5, v3, v2
	v_add_u32_e32 v4, 1, v1
	v_sub_u32_e32 v1, v1, v5
	v_add_u32_e32 v6, 1, v3
	v_cmp_ge_u32_e32 vcc, v1, v2
	v_sub_u32_e32 v5, v1, v2
	s_nop 0
	v_cndmask_b32_e32 v3, v3, v6, vcc
	v_cndmask_b32_e32 v1, v1, v5, vcc
	v_add_u32_e32 v5, 1, v3
	v_cmp_ge_u32_e32 vcc, v1, v2
	s_nop 1
	v_cndmask_b32_e32 v1, v3, v5, vcc
	v_mad_u64_u32 v[2:3], s[0:1], v2, v1, v[2:3]
	v_cmp_ne_u32_e32 vcc, v4, v2
	s_and_saveexec_b64 s[0:1], vcc
	s_xor_b64 s[0:1], exec, s[0:1]
	s_cbranch_execz .LBB0_229
	v_mov_b32_e32 v0, s27
	v_add_co_u32_e32 v2, vcc, 0x2000, v0
	v_mov_b32_e32 v0, s26
	s_nop 0
	v_addc_co_u32_e32 v3, vcc, 0, v0, vcc
	s_add_u32 s8, s38, 0x103500
	s_addc_u32 s9, s37, 0
	v_mov_b64_e32 v[2:3], s[8:9]
	flat_load_dword v0, v[2:3] sc1
	s_waitcnt vmcnt(0) lgkmcnt(0)
	v_cmp_eq_u32_e32 vcc, v0, v1
	s_and_saveexec_b64 s[4:5], vcc
	s_cbranch_execz .LBB0_228
	s_add_u32 s6, s38, 0x100200
	s_addc_u32 s7, s37, 0
	s_mov_b32 s28, 1
	s_mov_b64 s[10:11], 0
	s_branch .LBB0_220

; __device__ __forceinline__ unsigned xb_ld(unsigned* p)              { return __hip_atomic_load(p, __ATOMIC_RELAXED, __HIP_MEMORY_SCOPE_AGENT); }
; __device__ __forceinline__ unsigned xb_add(unsigned* p, unsigned v) { return __hip_atomic_fetch_add(p, v, __ATOMIC_RELAXED, __HIP_MEMORY_SCOPE_AGENT); }
; #define XB_SPIN(cond, bar) do { unsigned _sp = 0; while (cond) { __builtin_amdgcn_s_sleep(1); \
;     if ((++_sp & 255u) == 0u) { if (xb_ld(&(bar)[XB_TMO])) break; if (_sp > XB_SPIN_CAP) { atomicAdd(&(bar)[XB_TMO], 1u); break; } } } } while (0)
; __device__ __forceinline__ void xcd_barrier(const XcdBarrier& b) {
;     ...
;         const unsigned old = xb_add(&bar[XB_XSUB(b.x)], 1u);
;         const unsigned gen = old / nloc;
;         if (old + 1u == (gen + 1u) * nloc) {
;             __builtin_amdgcn_fence(__ATOMIC_RELEASE, "agent");
;             asm volatile("s_waitcnt vmcnt(0)" ::: "memory");
;             const unsigned og = xb_add(&bar[XB_TOP], 1u);
;             const unsigned tg = og / nx;
;             if (og + 1u == (tg + 1u) * nx) xb_add(&bar[XB_TOPGEN], 1u);
;             else XB_SPIN(xb_ld(&bar[XB_TOPGEN]) == tg, bar);
;             __builtin_amdgcn_fence(__ATOMIC_ACQUIRE, "agent");
;             xb_add(&bar[XB_XGEN(b.x)], 1u);
;             asm volatile("s_waitcnt vmcnt(0)" ::: "memory");
;         } else {
;             XB_SPIN(xb_ld(&bar[XB_XGEN(b.x)]) == gen, bar);
.LBB0_629:
	s_lshl_b32 s0, s40, 8
	s_add_u32 s0, s39, s0
	s_addc_u32 s1, s38, 0
	v_mov_b32_e32 v1, s0
	v_add_co_u32_e32 v4, vcc, 0x101000, v1
	v_mov_b32_e32 v1, s1
	s_nop 0
	v_addc_co_u32_e32 v5, vcc, 0, v1, vcc
	v_mov_b32_e32 v1, 1
	flat_atomic_add v1, v[4:5], v1 offset:1024 sc0
	v_cvt_f32_u32_e32 v3, v2
	v_sub_u32_e32 v4, 0, v2
	s_add_u32 s27, s0, 0x100000
	s_addc_u32 s26, s1, 0
	v_rcp_iflag_f32_e32 v3, v3
	s_nop 0
	v_mul_f32_e32 v3, 0x4f7ffffe, v3
	v_cvt_u32_f32_e32 v3, v3
	v_mul_lo_u32 v4, v4, v3
	v_mul_hi_u32 v4, v3, v4
	v_add_u32_e32 v3, v3, v4
	s_waitcnt vmcnt(0) lgkmcnt(0)
	v_mul_hi_u32 v3, v1, v3
	v_mul_lo_u32 v5, v3, v2
	v_add_u32_e32 v4, 1, v1
	v_sub_u32_e32 v1, v1, v5
	v_add_u32_e32 v6, 1, v3
	v_cmp_ge_u32_e32 vcc, v1, v2
	v_sub_u32_e32 v5, v1, v2
	s_nop 0
	v_cndmask_b32_e32 v3, v3, v6, vcc
	v_cndmask_b32_e32 v1, v1, v5, vcc
	v_add_u32_e32 v5, 1, v3
	v_cmp_ge_u32_e32 vcc, v1, v2
	s_nop 1
	v_cndmask_b32_e32 v1, v3, v5, vcc
	v_mad_u64_u32 v[2:3], s[0:1], v2, v1, v[2:3]
	v_cmp_ne_u32_e32 vcc, v4, v2
	s_and_saveexec_b64 s[0:1], vcc
	s_xor_b64 s[0:1], exec, s[0:1]
	s_cbranch_execz .LBB0_642
	v_mov_b32_e32 v0, s27
	v_add_co_u32_e32 v2, vcc, 0x2000, v0
	v_mov_b32_e32 v0, s26
	s_nop 0
	v_addc_co_u32_e32 v3, vcc, 0, v0, vcc
	s_add_u32 s8, s39, 0x103500
	s_addc_u32 s9, s38, 0
	v_mov_b64_e32 v[2:3], s[8:9]
	flat_load_dword v0, v[2:3] sc1
	s_waitcnt vmcnt(0) lgkmcnt(0)
	v_cmp_eq_u32_e32 vcc, v0, v1
	s_and_saveexec_b64 s[4:5], vcc
	s_cbranch_execz .LBB0_641
	s_add_u32 s6, s39, 0x100200
	s_addc_u32 s7, s38, 0
	s_mov_b32 s28, 1
	s_mov_b64 s[10:11], 0
	s_branch .LBB0_633

; __device__ __forceinline__ unsigned xb_ld(unsigned* p)              { return __hip_atomic_load(p, __ATOMIC_RELAXED, __HIP_MEMORY_SCOPE_AGENT); }
; __device__ __forceinline__ unsigned xb_add(unsigned* p, unsigned v) { return __hip_atomic_fetch_add(p, v, __ATOMIC_RELAXED, __HIP_MEMORY_SCOPE_AGENT); }
; #define XB_SPIN(cond, bar) do { unsigned _sp = 0; while (cond) { __builtin_amdgcn_s_sleep(1); \
;     if ((++_sp & 255u) == 0u) { if (xb_ld(&(bar)[XB_TMO])) break; if (_sp > XB_SPIN_CAP) { atomicAdd(&(bar)[XB_TMO], 1u); break; } } } } while (0)
; __device__ __forceinline__ void xcd_barrier(const XcdBarrier& b) {
;     ...
;         const unsigned old = xb_add(&bar[XB_XSUB(b.x)], 1u);
;         const unsigned gen = old / nloc;
;         if (old + 1u == (gen + 1u) * nloc) {
;             __builtin_amdgcn_fence(__ATOMIC_RELEASE, "agent");
;             asm volatile("s_waitcnt vmcnt(0)" ::: "memory");
;             const unsigned og = xb_add(&bar[XB_TOP], 1u);
;             const unsigned tg = og / nx;
;             if (og + 1u == (tg + 1u) * nx) xb_add(&bar[XB_TOPGEN], 1u);
;             else XB_SPIN(xb_ld(&bar[XB_TOPGEN]) == tg, bar);
;             __builtin_amdgcn_fence(__ATOMIC_ACQUIRE, "agent");
;             xb_add(&bar[XB_XGEN(b.x)], 1u);
;             asm volatile("s_waitcnt vmcnt(0)" ::: "memory");
;         } else {
;             XB_SPIN(xb_ld(&bar[XB_XGEN(b.x)]) == gen, bar);
.LBB0_696:
	s_lshl_b32 s0, s42, 8
	s_add_u32 s0, s39, s0
	s_addc_u32 s1, s38, 0
	v_mov_b32_e32 v1, s0
	v_add_co_u32_e32 v4, vcc, 0x101000, v1
	v_mov_b32_e32 v1, s1
	s_nop 0
	v_addc_co_u32_e32 v5, vcc, 0, v1, vcc
	v_mov_b32_e32 v1, 1
	flat_atomic_add v1, v[4:5], v1 offset:1024 sc0
	v_cvt_f32_u32_e32 v3, v2
	v_sub_u32_e32 v4, 0, v2
	s_add_u32 s27, s0, 0x100000
	s_addc_u32 s26, s1, 0
	v_rcp_iflag_f32_e32 v3, v3
	s_nop 0
	v_mul_f32_e32 v3, 0x4f7ffffe, v3
	v_cvt_u32_f32_e32 v3, v3
	v_mul_lo_u32 v4, v4, v3
	v_mul_hi_u32 v4, v3, v4
	v_add_u32_e32 v3, v3, v4
	s_waitcnt vmcnt(0) lgkmcnt(0)
	v_mul_hi_u32 v3, v1, v3
	v_mul_lo_u32 v5, v3, v2
	v_add_u32_e32 v4, 1, v1
	v_sub_u32_e32 v1, v1, v5
	v_add_u32_e32 v6, 1, v3
	v_cmp_ge_u32_e32 vcc, v1, v2
	v_sub_u32_e32 v5, v1, v2
	s_nop 0
	v_cndmask_b32_e32 v3, v3, v6, vcc
	v_cndmask_b32_e32 v1, v1, v5, vcc
	v_add_u32_e32 v5, 1, v3
	v_cmp_ge_u32_e32 vcc, v1, v2
	s_nop 1
	v_cndmask_b32_e32 v1, v3, v5, vcc
	v_mad_u64_u32 v[2:3], s[0:1], v2, v1, v[2:3]
	v_cmp_ne_u32_e32 vcc, v4, v2
	s_and_saveexec_b64 s[0:1], vcc
	s_xor_b64 s[0:1], exec, s[0:1]
	s_cbranch_execz .LBB0_709
	v_mov_b32_e32 v0, s27
	v_add_co_u32_e32 v2, vcc, 0x2000, v0
	v_mov_b32_e32 v0, s26
	s_nop 0
	v_addc_co_u32_e32 v3, vcc, 0, v0, vcc
	s_add_u32 s8, s39, 0x103500
	s_addc_u32 s9, s38, 0
	v_mov_b64_e32 v[2:3], s[8:9]
	flat_load_dword v0, v[2:3] sc1
	s_waitcnt vmcnt(0) lgkmcnt(0)
	v_cmp_eq_u32_e32 vcc, v0, v1
	s_and_saveexec_b64 s[4:5], vcc
	s_cbranch_execz .LBB0_708
	s_add_u32 s6, s39, 0x100200
	s_addc_u32 s7, s38, 0
	s_mov_b32 s28, 1
	s_mov_b64 s[10:11], 0
	s_branch .LBB0_700

; __device__ __forceinline__ unsigned xb_ld(unsigned* p)              { return __hip_atomic_load(p, __ATOMIC_RELAXED, __HIP_MEMORY_SCOPE_AGENT); }
; __device__ __forceinline__ unsigned xb_add(unsigned* p, unsigned v) { return __hip_atomic_fetch_add(p, v, __ATOMIC_RELAXED, __HIP_MEMORY_SCOPE_AGENT); }
; #define XB_SPIN(cond, bar) do { unsigned _sp = 0; while (cond) { __builtin_amdgcn_s_sleep(1); \
;     if ((++_sp & 255u) == 0u) { if (xb_ld(&(bar)[XB_TMO])) break; if (_sp > XB_SPIN_CAP) { atomicAdd(&(bar)[XB_TMO], 1u); break; } } } } while (0)
; __device__ __forceinline__ void xcd_barrier(const XcdBarrier& b) {
;     ...
;         const unsigned old = xb_add(&bar[XB_XSUB(b.x)], 1u);
;         const unsigned gen = old / nloc;
;         if (old + 1u == (gen + 1u) * nloc) {
;             __builtin_amdgcn_fence(__ATOMIC_RELEASE, "agent");
;             asm volatile("s_waitcnt vmcnt(0)" ::: "memory");
;             const unsigned og = xb_add(&bar[XB_TOP], 1u);
;             const unsigned tg = og / nx;
;             if (og + 1u == (tg + 1u) * nx) xb_add(&bar[XB_TOPGEN], 1u);
;             else XB_SPIN(xb_ld(&bar[XB_TOPGEN]) == tg, bar);
;             __builtin_amdgcn_fence(__ATOMIC_ACQUIRE, "agent");
;             xb_add(&bar[XB_XGEN(b.x)], 1u);
;             asm volatile("s_waitcnt vmcnt(0)" ::: "memory");
;         } else {
;             XB_SPIN(xb_ld(&bar[XB_XGEN(b.x)]) == gen, bar);
.LBB0_786:
	s_lshl_b32 s0, s42, 8
	s_add_u32 s0, s39, s0
	s_addc_u32 s1, s38, 0
	v_mov_b32_e32 v1, s0
	v_add_co_u32_e32 v4, vcc, 0x101000, v1
	v_mov_b32_e32 v1, s1
	s_nop 0
	v_addc_co_u32_e32 v5, vcc, 0, v1, vcc
	v_mov_b32_e32 v1, 1
	flat_atomic_add v1, v[4:5], v1 offset:1024 sc0
	v_cvt_f32_u32_e32 v3, v2
	v_sub_u32_e32 v4, 0, v2
	s_add_u32 s29, s0, 0x100000
	s_addc_u32 s28, s1, 0
	v_rcp_iflag_f32_e32 v3, v3
	s_nop 0
	v_mul_f32_e32 v3, 0x4f7ffffe, v3
	v_cvt_u32_f32_e32 v3, v3
	v_mul_lo_u32 v4, v4, v3
	v_mul_hi_u32 v4, v3, v4
	v_add_u32_e32 v3, v3, v4
	s_waitcnt vmcnt(0) lgkmcnt(0)
	v_mul_hi_u32 v3, v1, v3
	v_mul_lo_u32 v5, v3, v2
	v_add_u32_e32 v4, 1, v1
	v_sub_u32_e32 v1, v1, v5
	v_add_u32_e32 v6, 1, v3
	v_cmp_ge_u32_e32 vcc, v1, v2
	v_sub_u32_e32 v5, v1, v2
	s_nop 0
	v_cndmask_b32_e32 v3, v3, v6, vcc
	v_cndmask_b32_e32 v1, v1, v5, vcc
	v_add_u32_e32 v5, 1, v3
	v_cmp_ge_u32_e32 vcc, v1, v2
	s_nop 1
	v_cndmask_b32_e32 v1, v3, v5, vcc
	v_mad_u64_u32 v[2:3], s[0:1], v2, v1, v[2:3]
	v_cmp_ne_u32_e32 vcc, v4, v2
	s_and_saveexec_b64 s[0:1], vcc
	s_xor_b64 s[0:1], exec, s[0:1]
	s_cbranch_execz .LBB0_799
	v_mov_b32_e32 v0, s29
	v_add_co_u32_e32 v2, vcc, 0x2000, v0
	v_mov_b32_e32 v0, s28
	s_nop 0
	v_addc_co_u32_e32 v3, vcc, 0, v0, vcc
	s_add_u32 s10, s39, 0x103500
	s_addc_u32 s11, s38, 0
	v_mov_b64_e32 v[2:3], s[10:11]
	flat_load_dword v0, v[2:3] sc1
	s_waitcnt vmcnt(0) lgkmcnt(0)
	v_cmp_eq_u32_e32 vcc, v0, v1
	s_and_saveexec_b64 s[6:7], vcc
	s_cbranch_execz .LBB0_798
	s_add_u32 s8, s39, 0x100200
	s_addc_u32 s9, s38, 0
	s_mov_b32 s30, 1
	s_mov_b64 s[12:13], 0
	s_branch .LBB0_790

; __device__ __forceinline__ unsigned xb_ld(unsigned* p)              { return __hip_atomic_load(p, __ATOMIC_RELAXED, __HIP_MEMORY_SCOPE_AGENT); }
; __device__ __forceinline__ unsigned xb_add(unsigned* p, unsigned v) { return __hip_atomic_fetch_add(p, v, __ATOMIC_RELAXED, __HIP_MEMORY_SCOPE_AGENT); }
; #define XB_SPIN(cond, bar) do { unsigned _sp = 0; while (cond) { __builtin_amdgcn_s_sleep(1); \
;     if ((++_sp & 255u) == 0u) { if (xb_ld(&(bar)[XB_TMO])) break; if (_sp > XB_SPIN_CAP) { atomicAdd(&(bar)[XB_TMO], 1u); break; } } } } while (0)
; __device__ __forceinline__ void xcd_barrier(const XcdBarrier& b) {
;     ...
;         const unsigned old = xb_add(&bar[XB_XSUB(b.x)], 1u);
;         const unsigned gen = old / nloc;
;         if (old + 1u == (gen + 1u) * nloc) {
;             __builtin_amdgcn_fence(__ATOMIC_RELEASE, "agent");
;             asm volatile("s_waitcnt vmcnt(0)" ::: "memory");
;             const unsigned og = xb_add(&bar[XB_TOP], 1u);
;             const unsigned tg = og / nx;
;             if (og + 1u == (tg + 1u) * nx) xb_add(&bar[XB_TOPGEN], 1u);
;             else XB_SPIN(xb_ld(&bar[XB_TOPGEN]) == tg, bar);
;             __builtin_amdgcn_fence(__ATOMIC_ACQUIRE, "agent");
;             xb_add(&bar[XB_XGEN(b.x)], 1u);
;             asm volatile("s_waitcnt vmcnt(0)" ::: "memory");
;         } else {
;             XB_SPIN(xb_ld(&bar[XB_XGEN(b.x)]) == gen, bar);
.LBB0_851:
	s_lshl_b32 s0, s42, 8
	s_add_u32 s0, s41, s0
	s_addc_u32 s1, s40, 0
	v_mov_b32_e32 v1, s0
	v_add_co_u32_e32 v4, vcc, 0x101000, v1
	v_mov_b32_e32 v1, s1
	s_nop 0
	v_addc_co_u32_e32 v5, vcc, 0, v1, vcc
	v_mov_b32_e32 v1, 1
	flat_atomic_add v1, v[4:5], v1 offset:1024 sc0
	v_cvt_f32_u32_e32 v3, v2
	v_sub_u32_e32 v4, 0, v2
	s_add_u32 s29, s0, 0x100000
	s_addc_u32 s28, s1, 0
	v_rcp_iflag_f32_e32 v3, v3
	s_nop 0
	v_mul_f32_e32 v3, 0x4f7ffffe, v3
	v_cvt_u32_f32_e32 v3, v3
	v_mul_lo_u32 v4, v4, v3
	v_mul_hi_u32 v4, v3, v4
	v_add_u32_e32 v3, v3, v4
	s_waitcnt vmcnt(0) lgkmcnt(0)
	v_mul_hi_u32 v3, v1, v3
	v_mul_lo_u32 v5, v3, v2
	v_add_u32_e32 v4, 1, v1
	v_sub_u32_e32 v1, v1, v5
	v_add_u32_e32 v6, 1, v3
	v_cmp_ge_u32_e32 vcc, v1, v2
	v_sub_u32_e32 v5, v1, v2
	s_nop 0
	v_cndmask_b32_e32 v3, v3, v6, vcc
	v_cndmask_b32_e32 v1, v1, v5, vcc
	v_add_u32_e32 v5, 1, v3
	v_cmp_ge_u32_e32 vcc, v1, v2
	s_nop 1
	v_cndmask_b32_e32 v1, v3, v5, vcc
	v_mad_u64_u32 v[2:3], s[0:1], v2, v1, v[2:3]
	v_cmp_ne_u32_e32 vcc, v4, v2
	s_and_saveexec_b64 s[0:1], vcc
	s_xor_b64 s[0:1], exec, s[0:1]
	s_cbranch_execz .LBB0_864
	v_mov_b32_e32 v0, s29
	v_add_co_u32_e32 v2, vcc, 0x2000, v0
	v_mov_b32_e32 v0, s28
	s_nop 0
	v_addc_co_u32_e32 v3, vcc, 0, v0, vcc
	s_add_u32 s10, s41, 0x103500
	s_addc_u32 s11, s40, 0
	v_mov_b64_e32 v[2:3], s[10:11]
	flat_load_dword v0, v[2:3] sc1
	s_waitcnt vmcnt(0) lgkmcnt(0)
	v_cmp_eq_u32_e32 vcc, v0, v1
	s_and_saveexec_b64 s[6:7], vcc
	s_cbranch_execz .LBB0_863
	s_add_u32 s8, s41, 0x100200
	s_addc_u32 s9, s40, 0
	s_mov_b32 s30, 1
	s_mov_b64 s[12:13], 0
	s_branch .LBB0_855
